# HGRN prep tail: permlane gather of the four row products + packed LDS writes (KDT b64, QE/KE b32 pairs), on the v34 configuration
# baseline (speedup 1.0000x reference)
.LBB0_947:
	v_lshlrev_b32_e32 v0, 16, v45
	v_mul_f32_e32 v0, 0xbfb8aa3b, v0
	v_exp_f32_e32 v0, v0
	v_lshlrev_b32_e32 v1, 16, v44
	s_sub_i32 s80, 0, s62
	v_lshlrev_b32_e32 v42, 16, v42
	v_min_f32_e32 v0, 0x7149f2ca, v0
	v_add_f32_e32 v2, 1.0, v0
	v_rcp_f32_e32 v44, v2
	v_fma_f32 v0, v183, v0, 1.0
	v_rcp_f32_e32 v184, v0
	v_lshlrev_b32_e32 v40, 16, v40
	v_mul_f32_e32 v45, v0, v44
	v_fma_f32 v44, -v0, v44, 1.0
	v_lshlrev_b32_e32 v0, 16, v43
	v_mul_f32_e32 v0, 0xbfb8aa3b, v0
	v_exp_f32_e32 v0, v0
	v_cndmask_b32_e64 v184, v184, 1.0, s[58:59]
	v_mul_f32_e32 v2, v2, v184
	v_lshlrev_b32_e32 v38, 16, v38
	v_min_f32_e32 v0, 0x7149f2ca, v0
	v_add_f32_e32 v43, 1.0, v0
	v_rcp_f32_e32 v184, v43
	v_fma_f32 v0, v183, v0, 1.0
	v_rcp_f32_e32 v186, v0
	v_mul_f32_e32 v185, v0, v184
	v_fma_f32 v184, -v0, v184, 1.0
	v_lshlrev_b32_e32 v0, 16, v41
	v_mul_f32_e32 v0, 0xbfb8aa3b, v0
	v_exp_f32_e32 v0, v0
	v_cndmask_b32_e64 v186, v186, 1.0, s[58:59]
	v_mul_f32_e32 v43, v43, v186
	v_mul_f32_e32 v185, v45, v185
	v_min_f32_e32 v0, 0x7149f2ca, v0
	v_add_f32_e32 v41, 1.0, v0
	v_rcp_f32_e32 v186, v41
	v_fma_f32 v0, v183, v0, 1.0
	v_rcp_f32_e32 v188, v0
	v_mul_f32_e32 v43, v2, v43
	v_mul_f32_e32 v187, v0, v186
	v_fma_f32 v186, -v0, v186, 1.0
	v_lshlrev_b32_e32 v0, 16, v39
	v_mul_f32_e32 v0, 0xbfb8aa3b, v0
	v_exp_f32_e32 v0, v0
	v_cndmask_b32_e64 v188, v188, 1.0, s[58:59]
	v_mul_f32_e32 v41, v41, v188
	v_mul_f32_e32 v187, v185, v187
	v_min_f32_e32 v0, 0x7149f2ca, v0
	v_add_f32_e32 v39, 1.0, v0
	v_fma_f32 v0, v183, v0, 1.0
	v_rcp_f32_e32 v188, v39
	v_rcp_f32_e32 v190, v0
	v_mul_f32_e32 v41, v43, v41
	v_mul_f32_e32 v189, v0, v188
	v_cndmask_b32_e64 v190, v190, 1.0, s[58:59]
	v_mul_f32_e32 v39, v39, v190
	v_mul_f32_e32 v189, v187, v189
	v_fma_f32 v188, -v0, v188, 1.0
	v_mul_f32_e32 v39, v41, v39
	v_mov_b32_e32 v228, v189
	v_mov_b32_e32 v229, v189
	v_mov_b32_e32 v232, v39
	v_mov_b32_e32 v233, v39
	v_cmp_eq_u32_e32 vcc, 12, v54
	v_permlane16_swap_b32_e32 v228, v229
	v_permlane16_swap_b32_e32 v232, v233
	v_mov_b32_e32 v230, v228
	v_mov_b32_e32 v231, v229
	v_mov_b32_e32 v234, v232
	v_mov_b32_e32 v235, v233
	s_nop 1
	v_permlane32_swap_b32_e32 v228, v230
	v_permlane32_swap_b32_e32 v229, v231
	v_permlane32_swap_b32_e32 v232, v234
	v_permlane32_swap_b32_e32 v233, v235
	v_mul_f32_e32 v240, v228, v229
	v_mul_f32_e32 v241, v232, v233
	v_cndmask_b32_e64 v236, 1.0, v228, s[40:41]
	v_cndmask_b32_e64 v237, 1.0, v232, s[40:41]
	v_mul_f32_e32 v239, v240, v230
	v_mul_f32_e32 v242, v241, v234
	v_cndmask_b32_e64 v236, v236, v240, s[42:43]
	v_cndmask_b32_e64 v237, v237, v241, s[42:43]
	v_mul_f32_e32 v238, v239, v231
	v_cndmask_b32_e32 v236, v236, v239, vcc
	v_cndmask_b32_e32 v237, v237, v242, vcc
	v_mul_f32_e32 v45, v45, v236
	v_mul_f32_e32 v2, v2, v237
	v_mul_f32_e32 v185, v185, v236
	v_mul_f32_e32 v43, v43, v237
	v_mul_f32_e32 v187, v187, v236
	v_mul_f32_e32 v41, v41, v237
	v_mul_f32_e32 v189, v189, v236
	v_mul_f32_e32 v39, v39, v237
	v_mul_f32_e32 v1, v45, v1
	v_min_f32_e32 v2, 0x799a130c, v2
	v_mul_f32_e32 v42, v185, v42
	v_min_f32_e32 v43, 0x799a130c, v43
	v_mul_f32_e32 v40, v187, v40
	v_min_f32_e32 v41, 0x799a130c, v41
	v_mul_f32_e32 v38, v189, v38
	v_min_f32_e32 v39, 0x799a130c, v39
	v_mul_f32_e32 v44, v44, v2
	v_mul_f32_e32 v184, v184, v43
	v_mul_f32_e32 v186, v186, v41
	v_mul_f32_e32 v188, v188, v39
	v_mul_f32_e32 v2, v44, v238
	v_mul_f32_e32 v43, v184, v238
	v_mul_f32_e32 v41, v186, v238
	v_mul_f32_e32 v39, v188, v238
	v_cvt_pk_bf16_f32 v240, v2, v43
	v_cvt_pk_bf16_f32 v241, v41, v39
	v_lshlrev_b32_e32 v239, 1, v54
	v_add3_u32 v239, s80, v63, v239
	ds_write_b64 v239, v[240:241] offset:31232
	s_and_saveexec_b64 s[12:13], s[44:45]
	v_lshl_add_u32 v242, v52, 2, s80
	ds_write_b32 v242, v238 offset:43520
	s_or_b64 exec, exec, s[12:13]
	s_mov_b32 s12, 0xaaaaaaaa
	s_mov_b32 s13, 0xaaaaaaaa
	v_and_b32_e32 v243, 1, v52
	v_lshl_add_u32 v244, v140, 1, s80
	v_mov_b32_e32 v245, 0x21e
	v_mad_u32_u24 v244, v243, v245, v244
	v_cndmask_b32_e64 v208, v40, v1, s[12:13]
	v_cndmask_b32_e64 v209, v38, v42, s[12:13]
	v_cndmask_b32_e64 v246, v1, v40, s[12:13]
	v_cndmask_b32_e64 v247, v42, v38, s[12:13]
	v_mov_b32_dpp v210, v208 quad_perm:[1,0,3,2] row_mask:0xf bank_mask:0xf
	v_mov_b32_dpp v211, v209 quad_perm:[1,0,3,2] row_mask:0xf bank_mask:0xf
	v_cndmask_b32_e64 v208, v246, v210, s[12:13]
	v_cndmask_b32_e64 v246, v210, v246, s[12:13]
	v_cndmask_b32_e64 v209, v247, v211, s[12:13]
	v_cndmask_b32_e64 v247, v211, v247, s[12:13]
	v_cvt_pk_bf16_f32 v208, v208, v246
	v_cvt_pk_bf16_f32 v209, v209, v247
	ds_write_b32 v244, v208 offset:22528
	ds_write_b32 v244, v209 offset:22800
	v_cndmask_b32_e64 v208, v186, v44, s[12:13]
	v_cndmask_b32_e64 v209, v188, v184, s[12:13]
	v_cndmask_b32_e64 v246, v44, v186, s[12:13]
	v_cndmask_b32_e64 v247, v184, v188, s[12:13]
	v_mov_b32_dpp v210, v208 quad_perm:[1,0,3,2] row_mask:0xf bank_mask:0xf
	v_mov_b32_dpp v211, v209 quad_perm:[1,0,3,2] row_mask:0xf bank_mask:0xf
	v_cndmask_b32_e64 v208, v246, v210, s[12:13]
	v_cndmask_b32_e64 v246, v210, v246, s[12:13]
	v_cndmask_b32_e64 v209, v247, v211, s[12:13]
	v_cndmask_b32_e64 v247, v211, v247, s[12:13]
	v_cvt_pk_bf16_f32 v208, v208, v246
	v_cvt_pk_bf16_f32 v209, v209, v247
	ds_write_b32 v244, v208 offset:26880
	ds_write_b32 v244, v209 offset:27152
	v_cndmask_b32_e64 v247, v37, v36, s[12:13]
	v_cndmask_b32_e64 v246, v36, v37, s[12:13]
	v_mov_b32_e32 v212, 0x5040100
	v_mov_b32_e32 v213, 0x7060302
	v_mov_b32_dpp v208, v247 quad_perm:[1,0,3,2] row_mask:0xf bank_mask:0xf
	v_lshl_add_u32 v209, v67, 1, s80
	v_mov_b32_e32 v210, 94
	v_mad_u32_u24 v209, v243, v210, v209
	v_cndmask_b32_e64 v247, v246, v208, s[12:13]
	v_cndmask_b32_e64 v246, v208, v246, s[12:13]
	v_perm_b32 v211, v246, v247, v212
	v_perm_b32 v214, v246, v247, v213
	ds_write_b32 v209, v211 offset:37376
	ds_write_b32 v209, v214 offset:37424

.LBB0_982:
	v_lshlrev_b32_e32 v43, 16, v205
	v_mul_f32_e32 v43, 0xbfb8aa3b, v43
	v_exp_f32_e32 v43, v43
	v_lshlrev_b32_e32 v44, 16, v206
	s_sub_i32 s83, 0, s82
	v_min_f32_e32 v43, 0x7149f2ca, v43
	v_add_f32_e32 v45, 1.0, v43
	v_rcp_f32_e32 v46, v45
	v_fma_f32 v43, v183, v43, 1.0
	v_rcp_f32_e32 v48, v43
	v_mul_f32_e32 v47, v43, v46
	v_fma_f32 v46, -v43, v46, 1.0
	v_lshlrev_b32_e32 v43, 16, v203
	v_mul_f32_e32 v43, 0xbfb8aa3b, v43
	v_exp_f32_e32 v43, v43
	v_cndmask_b32_e64 v48, v48, 1.0, s[56:57]
	v_mul_f32_e32 v45, v45, v48
	v_lshlrev_b32_e32 v48, 16, v204
	v_min_f32_e32 v43, 0x7149f2ca, v43
	v_add_f32_e32 v49, 1.0, v43
	v_rcp_f32_e32 v184, v49
	v_fma_f32 v43, v183, v43, 1.0
	v_rcp_f32_e32 v186, v43
	v_mul_f32_e32 v185, v43, v184
	v_fma_f32 v184, -v43, v184, 1.0
	v_lshlrev_b32_e32 v43, 16, v201
	v_mul_f32_e32 v43, 0xbfb8aa3b, v43
	v_exp_f32_e32 v43, v43
	v_cndmask_b32_e64 v186, v186, 1.0, s[56:57]
	v_mul_f32_e32 v49, v49, v186
	v_mul_f32_e32 v185, v47, v185
	v_min_f32_e32 v43, 0x7149f2ca, v43
	v_add_f32_e32 v187, 1.0, v43
	v_rcp_f32_e32 v188, v187
	v_fma_f32 v43, v183, v43, 1.0
	v_rcp_f32_e32 v190, v43
	v_mul_f32_e32 v49, v45, v49
	v_mul_f32_e32 v189, v43, v188
	v_fma_f32 v188, -v43, v188, 1.0
	v_lshlrev_b32_e32 v43, 16, v199
	v_mul_f32_e32 v43, 0xbfb8aa3b, v43
	v_exp_f32_e32 v43, v43
	v_cndmask_b32_e64 v190, v190, 1.0, s[56:57]
	v_mul_f32_e32 v187, v187, v190
	v_mul_f32_e32 v189, v185, v189
	v_min_f32_e32 v43, 0x7149f2ca, v43
	v_add_f32_e32 v191, 1.0, v43
	v_fma_f32 v43, v183, v43, 1.0
	v_rcp_f32_e32 v192, v191
	v_rcp_f32_e32 v194, v43
	v_mul_f32_e32 v187, v49, v187
	v_lshlrev_b32_e32 v186, 16, v202
	v_mul_f32_e32 v193, v43, v192
	v_cndmask_b32_e64 v194, v194, 1.0, s[56:57]
	v_mul_f32_e32 v191, v191, v194
	v_mul_f32_e32 v193, v189, v193
	v_fma_f32 v192, -v43, v192, 1.0
	v_mul_f32_e32 v191, v187, v191
	v_lshlrev_b32_e32 v190, 16, v200
	v_mov_b32_e32 v228, v193
	v_mov_b32_e32 v229, v193
	v_mov_b32_e32 v232, v191
	v_mov_b32_e32 v233, v191
	v_cmp_eq_u32_e32 vcc, 12, v54
	v_permlane16_swap_b32_e32 v228, v229
	v_permlane16_swap_b32_e32 v232, v233
	v_mov_b32_e32 v230, v228
	v_mov_b32_e32 v231, v229
	v_mov_b32_e32 v234, v232
	v_mov_b32_e32 v235, v233
	s_nop 1
	v_permlane32_swap_b32_e32 v228, v230
	v_permlane32_swap_b32_e32 v229, v231
	v_permlane32_swap_b32_e32 v232, v234
	v_permlane32_swap_b32_e32 v233, v235
	v_mul_f32_e32 v240, v228, v229
	v_mul_f32_e32 v241, v232, v233
	v_cndmask_b32_e64 v236, 1.0, v228, s[40:41]
	v_cndmask_b32_e64 v237, 1.0, v232, s[40:41]
	v_mul_f32_e32 v239, v240, v230
	v_mul_f32_e32 v242, v241, v234
	v_cndmask_b32_e64 v236, v236, v240, s[42:43]
	v_cndmask_b32_e64 v237, v237, v241, s[42:43]
	v_mul_f32_e32 v238, v239, v231
	v_cndmask_b32_e32 v236, v236, v239, vcc
	v_cndmask_b32_e32 v237, v237, v242, vcc
	v_mul_f32_e32 v47, v47, v236
	v_mul_f32_e32 v45, v45, v237
	v_mul_f32_e32 v185, v185, v236
	v_mul_f32_e32 v49, v49, v237
	v_mul_f32_e32 v189, v189, v236
	v_mul_f32_e32 v187, v187, v237
	v_mul_f32_e32 v193, v193, v236
	v_mul_f32_e32 v191, v191, v237
	v_mul_f32_e32 v44, v47, v44
	v_min_f32_e32 v45, 0x799a130c, v45
	v_mul_f32_e32 v48, v185, v48
	v_min_f32_e32 v49, 0x799a130c, v49
	v_mul_f32_e32 v186, v189, v186
	v_min_f32_e32 v187, 0x799a130c, v187
	v_mul_f32_e32 v190, v193, v190
	v_min_f32_e32 v191, 0x799a130c, v191
	v_mul_f32_e32 v46, v46, v45
	v_mul_f32_e32 v184, v184, v49
	v_mul_f32_e32 v188, v188, v187
	v_mul_f32_e32 v192, v192, v191
	v_mul_f32_e32 v45, v46, v238
	v_mul_f32_e32 v49, v184, v238
	v_mul_f32_e32 v187, v188, v238
	v_mul_f32_e32 v191, v192, v238
	v_cvt_pk_bf16_f32 v240, v45, v49
	v_cvt_pk_bf16_f32 v241, v187, v191
	v_lshlrev_b32_e32 v239, 1, v54
	v_add3_u32 v239, s83, v63, v239
	ds_write_b64 v239, v[240:241] offset:31232
	s_and_saveexec_b64 s[14:15], s[44:45]
	v_lshl_add_u32 v242, v52, 2, s83
	ds_write_b32 v242, v238 offset:43520
	s_or_b64 exec, exec, s[14:15]
	s_mov_b32 s14, 0xaaaaaaaa
	s_mov_b32 s15, 0xaaaaaaaa
	v_and_b32_e32 v243, 1, v52
	v_lshl_add_u32 v244, v140, 1, s83
	v_mov_b32_e32 v245, 0x21e
	v_mad_u32_u24 v244, v243, v245, v244
	v_cndmask_b32_e64 v208, v186, v44, s[14:15]
	v_cndmask_b32_e64 v209, v190, v48, s[14:15]
	v_cndmask_b32_e64 v246, v44, v186, s[14:15]
	v_cndmask_b32_e64 v247, v48, v190, s[14:15]
	v_mov_b32_dpp v210, v208 quad_perm:[1,0,3,2] row_mask:0xf bank_mask:0xf
	v_mov_b32_dpp v211, v209 quad_perm:[1,0,3,2] row_mask:0xf bank_mask:0xf
	v_cndmask_b32_e64 v208, v246, v210, s[14:15]
	v_cndmask_b32_e64 v246, v210, v246, s[14:15]
	v_cndmask_b32_e64 v209, v247, v211, s[14:15]
	v_cndmask_b32_e64 v247, v211, v247, s[14:15]
	v_cvt_pk_bf16_f32 v208, v208, v246
	v_cvt_pk_bf16_f32 v209, v209, v247
	ds_write_b32 v244, v208 offset:22528
	ds_write_b32 v244, v209 offset:22800
	v_cndmask_b32_e64 v208, v188, v46, s[14:15]
	v_cndmask_b32_e64 v209, v192, v184, s[14:15]
	v_cndmask_b32_e64 v246, v46, v188, s[14:15]
	v_cndmask_b32_e64 v247, v184, v192, s[14:15]
	v_mov_b32_dpp v210, v208 quad_perm:[1,0,3,2] row_mask:0xf bank_mask:0xf
	v_mov_b32_dpp v211, v209 quad_perm:[1,0,3,2] row_mask:0xf bank_mask:0xf
	v_cndmask_b32_e64 v208, v246, v210, s[14:15]
	v_cndmask_b32_e64 v246, v210, v246, s[14:15]
	v_cndmask_b32_e64 v209, v247, v211, s[14:15]
	v_cndmask_b32_e64 v247, v211, v247, s[14:15]
	v_cvt_pk_bf16_f32 v208, v208, v246
	v_cvt_pk_bf16_f32 v209, v209, v247
	ds_write_b32 v244, v208 offset:26880
	ds_write_b32 v244, v209 offset:27152
	v_cndmask_b32_e64 v247, v149, v148, s[14:15]
	v_cndmask_b32_e64 v246, v148, v149, s[14:15]
	v_mov_b32_e32 v212, 0x5040100
	v_mov_b32_e32 v213, 0x7060302
	v_mov_b32_dpp v208, v247 quad_perm:[1,0,3,2] row_mask:0xf bank_mask:0xf
	v_lshl_add_u32 v209, v67, 1, s83
	v_mov_b32_e32 v210, 94
	v_mad_u32_u24 v209, v243, v210, v209
	v_cndmask_b32_e64 v247, v246, v208, s[14:15]
	v_cndmask_b32_e64 v246, v208, v246, s[14:15]
	v_perm_b32 v211, v246, v247, v212
	v_perm_b32 v214, v246, v247, v213
	ds_write_b32 v209, v211 offset:37376
	ds_write_b32 v209, v214 offset:37424
